# gate|up GEMM: next-unit tile coordinates from an incremental index (+32 per unit), one magic multiply and a shift instead of the full remap + two generic divisions
# baseline (speedup 1.0000x reference)
; __device__ __forceinline__ int ltid() { int t = threadIdx.x; asm volatile("" : "+v"(t)); return t; }
; #define PG8_BAR __builtin_amdgcn_s_barrier()
;     __device__ bool next(int i, Unit& u) const {
;         const long L = (long)i * G + c; if (L >= nwg) return false;
;         int wgid = (int)L; { const int q = nwg / NXCD, r = nwg % NXCD, xcd = wgid % NXCD, off = wgid / NXCD; wgid = (xcd < r ? xcd * (q + 1) : r * (q + 1) + (xcd - r) * q) + off; }
;         const int nig = WGM * nN, gid = wgid / nig, fm = gid * WGM, gsz = (nM - fm) < WGM ? (nM - fm) : WGM;
;         u.pm = fm + ((wgid % nig) % gsz); u.pn = (wgid % nig) / gsz; u.kp = 0; return true;
; template <class Epi, class Sched = StaticOrder, bool ALIGN_EPI = true>
; __device__ __forceinline__ void gemm_phase(LAS unsigned char* lds, const Gemm g, const Sched& S, const Epi& E) {
;     const int tid = ltid(), wid = __builtin_amdgcn_readfirstlane(tid >> 6), lane = tid & 63, wr = wid >> 2, wc = wid & 3, fr = lane & 15, fq = lane >> 4;
;     const int K = g.K, nt = K / BK;
;     unsigned voffA[2], voffB[2];
; #pragma unroll
;     for (int i = 0; i < 2; ++i) { int R, C; stage_rc(tid * 16 + i * 8192, R, C); const int Rb = Epi::PERM ? ((R & ~31) + perm32(R & 31)) : R;
;         voffA[i] = (unsigned)(R * g.ld + C) * 2u; voffB[i] = (unsigned)(Rb * g.ld + C) * 2u; }
;     const size_t kstep = (size_t)(BK * 2);
;     const size_t hstep = (size_t)HALF * g.ld * 2;
;     const size_t tstep = 2 * hstep;
;     const unsigned ldsw = (unsigned)wid * 1024u;
;     const int aoff = lds_byte(wr * 64 + fr, fq * 8), boff = lds_byte(wc * 32 + fr, fq * 8);
;     ...
;     Unit cur, nxt; int ui = 0;
;     if (!S.next(0, cur)) return;
;     f32x4 acc[2][2][4][2];
; #pragma unroll
;     for (int a = 0; a < 2; ++a)
; #pragma unroll
;         for (int b = 0; b < 2; ++b)
; #pragma unroll
;             for (int m = 0; m < 4; ++m)
; #pragma unroll
;                 for (int n = 0; n < 2; ++n) acc[a][b][m][n] = (f32x4){0.f, 0.f, 0.f, 0.f};
;     bf16x8 At[4][2], B0[2][2], B1[2][2];
;     const char* cA = (const char*)g.A + (size_t)cur.pm * tstep + (size_t)cur.kp * K * 2; const char* cB = (const char*)g.Bt + (size_t)cur.pn * tstep + (size_t)cur.kp * K * 2;
;     PG8_STAGE(PG8_SB(0, 0), cB, voffB); PG8_STAGE(PG8_SB(0, 1), cB + hstep, voffB); PG8_STAGE(PG8_SA(0, 0), cA, voffA); PG8_STAGE(PG8_SA(0, 1), cA + hstep, voffA);
;     if (wr == 1) PG8_BAR;
.LBB0_457:
	s_nop 0
	v_readlane_b32 s0, v251, 12
	v_readlane_b32 s1, v251, 13
	s_andn2_b64 vcc, exec, s[0:1]
	s_cbranch_vccnz .LBB0_474
	s_cmp_eq_u32 s71, 8
	v_readlane_b32 s2, v251, 2
	s_cselect_b64 s[0:1], -1, 0
	v_readlane_b32 s3, v251, 3
	s_and_b64 s[0:1], s[2:3], s[0:1]
	s_and_b64 s[0:1], s[0:1], exec
	s_movk_i32 s0, 0xc2
	s_cselect_b32 s80, 0xc0, s0
	s_mul_i32 s18, s80, 44
	s_mov_b32 s81, s22
	v_mov_b32_e32 v16, v155
	s_cmp_ge_i32 s81, s18
	v_readfirstlane_b32 s9, v16
	s_cbranch_scc1 .LBB0_474
	v_lshlrev_b32_e32 v1, 4, v16
	v_add_u32_e32 v2, 0x2000, v1
	v_ashrrev_i32_e32 v3, 31, v2
	v_lshrrev_b32_e32 v3, 22, v3
	v_add_u32_e32 v3, v2, v3
	v_ashrrev_i32_e32 v10, 10, v3
	v_mul_i32_i24_e32 v3, 0x400, v10
	v_sub_u32_e32 v2, v2, v3
	v_lshrrev_b32_e32 v3, 4, v2
	v_bitop3_b32 v2, v3, v2, 32 bitop3:0x6c
	s_ashr_i32 s7, s9, 6
	v_ashrrev_i32_e32 v3, 31, v2
	s_ashr_i32 s8, s9, 8
	s_lshl_b32 s92, s7, 10
	v_lshrrev_b32_e32 v3, 26, v3
	s_cmp_eq_u32 s71, 0
	v_add_u32_e32 v3, v2, v3
	v_lshlrev_b32_e32 v4, 3, v10
	s_cselect_b32 s0, 0, 0x4200000
	v_readlane_b32 s1, v252, 8
	v_ashrrev_i32_e32 v11, 6, v3
	v_and_b32_e32 v4, -16, v4
	s_add_u32 s77, s1, s0
	v_readlane_b32 s0, v252, 9
	v_add_u32_e32 v4, v11, v4
	s_addc_u32 s93, s0, 0
	v_and_b32_e32 v5, 3, v11
	s_mov_b32 s0, 0xfffe0
	v_lshrrev_b32_e32 v6, 2, v4
	v_lshlrev_b32_e32 v7, 1, v4
	v_and_b32_e32 v3, 0xc0, v3
	v_and_or_b32 v5, v4, s0, v5
	v_and_b32_e32 v6, 4, v6
	v_and_b32_e32 v7, 24, v7
	v_sub_u32_e32 v2, v2, v3
	v_or3_b32 v5, v5, v6, v7
	v_lshlrev_b32_e32 v6, 5, v10
	v_ashrrev_i16_sdwa v2, v198, sext(v2) dst_sel:DWORD dst_unused:UNUSED_PAD src0_sel:DWORD src1_sel:BYTE_0
	v_and_b32_e32 v6, 32, v6
	v_bfe_i32 v12, v2, 0, 16
	v_add_lshl_u32 v2, v6, v12, 1
	v_lshl_add_u32 v130, v5, 12, v2
	v_lshl_add_u32 v132, v4, 12, v2
	v_bfe_i32 v2, v16, 27, 1
	v_lshrrev_b32_e32 v2, 22, v2
	v_add_u32_e32 v2, v1, v2
	v_and_b32_e32 v2, 0xfffffc00, v2
	v_sub_u32_e32 v1, v1, v2
	v_lshrrev_b32_e32 v2, 4, v1
	v_bitop3_b32 v2, v2, v1, 32 bitop3:0x6c
	v_ashrrev_i32_e32 v1, 31, v1
	v_lshrrev_b32_e32 v1, 26, v1
	v_add_u32_e32 v1, v2, v1
	v_ashrrev_i32_e32 v13, 6, v1
	v_ashrrev_i32_e32 v1, 31, v16
	v_lshrrev_b32_e32 v1, 26, v1
	v_add_u32_e32 v1, v16, v1
	v_ashrrev_i32_e32 v14, 6, v1
	v_lshlrev_b32_e32 v1, 3, v14
	v_and_b32_e32 v1, -16, v1
	v_add_u32_e32 v1, v13, v1
	v_and_b32_e32 v3, 3, v13
	s_ashr_i32 s22, s81, 31
	v_and_or_b32 v3, v1, s0, v3
	s_lshr_b32 s0, s22, 29
	s_add_i32 s0, s81, s0
	s_lshr_b32 s79, s18, 3
	s_ashr_i32 s1, s0, 3
	s_and_b32 s0, s0, -8
	s_add_i32 s70, s79, 1
	s_sub_i32 s0, s81, s0
	s_cmp_lt_i32 s0, 0
	s_cselect_b32 s2, s70, s79
	s_mul_i32 s0, s0, s2
	s_add_i32 s0, s0, s1
	s_mov_b32 s101, s0
	v_lshrrev_b32_e32 v4, 2, v1
	v_lshlrev_b32_e32 v5, 1, v1
	s_mul_hi_i32 s1, s0, 0x2e8ba2e9
	v_and_b32_e32 v4, 4, v4
	v_and_b32_e32 v5, 24, v5
	s_lshr_b32 s2, s1, 31
	s_ashr_i32 s1, s1, 5
	v_or3_b32 v3, v3, v4, v5
	v_mul_i32_i24_e32 v5, 64, v13
	s_add_i32 s1, s1, s2
	v_sub_u32_e32 v2, v2, v5
	s_lshl_b32 s2, s1, 2
	v_lshlrev_b32_e32 v4, 5, v14
	v_ashrrev_i16_sdwa v2, v198, sext(v2) dst_sel:DWORD dst_unused:UNUSED_PAD src0_sel:DWORD src1_sel:BYTE_0
	s_sub_i32 s3, s80, s2
	v_and_b32_e32 v4, 32, v4
	v_bfe_i32 v15, v2, 0, 16
	s_min_u32 s3, s3, 4
	s_mulk_i32 s1, 0xb0
	v_add_lshl_u32 v2, v4, v15, 1
	s_sub_i32 s4, s0, s1
	v_cvt_f32_ubyte0_e32 v4, s3
	v_lshl_add_u32 v134, v3, 12, v2
	v_cvt_f32_i32_e32 v3, s4
	v_rcp_iflag_f32_e32 v5, v4
	v_lshl_add_u32 v136, v1, 12, v2
	s_ashr_i32 s0, s4, 30
	s_or_b32 s5, s0, 1
	v_mul_f32_e32 v1, v3, v5
	v_trunc_f32_e32 v1, v1
	v_fma_f32 v2, -v1, v4, v3
	v_cvt_i32_f32_e32 v1, v1
	v_cmp_ge_f32_e64 s[0:1], |v2|, v4
	s_and_b64 s[0:1], s[0:1], exec
	s_cselect_b32 s0, s5, 0
	v_readfirstlane_b32 s1, v1
	s_add_i32 s12, s1, s0
	s_mul_i32 s0, s12, s3
	s_sub_i32 s0, s4, s0
	s_sext_i32_i16 s0, s0
	s_add_i32 s0, s2, s0
	s_ashr_i32 s1, s0, 31
	s_bfe_i64 s[4:5], s[12:13], 0x100000
	s_lshl_b64 s[2:3], s[0:1], 20
	s_lshl_b64 s[4:5], s[4:5], 20
	s_add_u32 s46, s77, s4
	s_addc_u32 s47, s93, s5
	s_add_i32 s23, s92, 0
	s_add_i32 m0, s23, 0x10000
	v_mov_b32_e32 v135, v0
	global_load_lds_dwordx4 v134, s[46:47]
	s_add_i32 m0, s23, 0x12000
	s_add_u32 s4, s46, 0x80000
	global_load_lds_dwordx4 v130, s[46:47]
	s_addc_u32 s5, s47, 0
	s_add_i32 m0, s23, 0x14000
	v_mov_b32_e32 v131, v0
	global_load_lds_dwordx4 v134, s[4:5]
	s_add_i32 m0, s23, 0x16000
	v_mov_b32_e32 v137, v0
	global_load_lds_dwordx4 v130, s[4:5]
	v_readlane_b32 s4, v252, 0
	v_readlane_b32 s5, v252, 1
	s_add_u32 s44, s4, s2
	s_addc_u32 s45, s5, s3
	s_add_i32 s4, s23, 0x2000
	s_mov_b32 m0, s23
	s_add_u32 s2, s44, 0x80000
	global_load_lds_dwordx4 v136, s[44:45]
	s_mov_b32 m0, s4
	s_addc_u32 s3, s45, 0
	s_add_i32 s5, s23, 0x4000
	global_load_lds_dwordx4 v132, s[44:45]
	s_mov_b32 m0, s5
	s_add_i32 s6, s23, 0x6000
	global_load_lds_dwordx4 v136, s[2:3]
	s_mov_b32 m0, s6
	v_mov_b32_e32 v133, v0
	global_load_lds_dwordx4 v132, s[2:3]
	s_cmp_eq_u32 s8, 1
	v_lshl_add_u64 v[8:9], s[46:47], 0, v[134:135]
	v_lshl_add_u64 v[6:7], s[46:47], 0, v[130:131]
	v_lshl_add_u64 v[2:3], s[44:45], 0, v[136:137]
	s_cselect_b64 s[2:3], -1, 0
	s_cmp_lg_u32 s8, 1
	v_lshl_add_u64 v[4:5], s[44:45], 0, v[132:133]
	s_cbranch_scc1 .LBB0_461
	s_barrier

;     __device__ bool next(int i, Unit& u) const { const int idx = i * G + c; if (idx >= 64) return false; u.kp = idx & 3; u.pn = (idx >> 2) & 7; u.pm = 192 + (idx >> 5); return true; }
;     __device__ bool next(int i, Unit& u) const {
;         const long L = (long)i * G + c; if (L >= nwg) return false;
;         int wgid = (int)L; { const int q = nwg / NXCD, r = nwg % NXCD, xcd = wgid % NXCD, off = wgid / NXCD; wgid = (xcd < r ? xcd * (q + 1) : r * (q + 1) + (xcd - r) * q) + off; }
;         const int nig = WGM * nN, gid = wgid / nig, fm = gid * WGM, gsz = (nM - fm) < WGM ? (nM - fm) : WGM;
;         u.pm = fm + ((wgid % nig) % gsz); u.pn = (wgid % nig) / gsz; u.kp = 0; return true;
;     }
.LBB0_464:
	s_add_i32 s9, s9, 1
	s_mul_i32 s10, s9, s68
	s_mul_hi_u32 s11, s9, s29
	s_add_i32 s11, s11, s10
	s_mul_i32 s10, s9, s29
	s_add_u32 s36, s10, s81
	s_addc_u32 s37, s11, s22
	v_mov_b64_e32 v[2:3], s[18:19]
	v_cmp_ge_i64_e32 vcc, s[36:37], v[2:3]
	v_cmp_lt_i64_e64 s[40:41], s[36:37], v[2:3]
	s_cbranch_vccnz .LBB0_466
	s_add_i32 s101, s101, 32
	s_mul_hi_i32 s11, s101, 0x2e8ba2e9
	s_lshr_b32 s16, s11, 31
	s_ashr_i32 s11, s11, 5
	s_add_i32 s11, s11, s16
	s_lshl_b32 s16, s11, 2
	s_sub_i32 s17, s80, s16
	s_min_i32 s17, s17, 4
	s_mulk_i32 s11, 0xb0
	s_sub_i32 s10, s101, s11
	s_ff1_i32_b32 s11, s17
	s_lshr_b32 s20, s10, s11
	s_lshl_b32 s11, s20, s11
	s_sub_i32 s10, s10, s11
	s_add_i32 s30, s10, s16

; #define LAS __attribute__((address_space(3)))
; __global__ void __launch_bounds__(512, 2) fwd_megakernel(Args a) {
;     extern __shared__ __attribute__((aligned(16))) unsigned char shm[];
;     LAS unsigned char* lds = (LAS unsigned char*)shm;
	.amdhsa_kernel _Z14fwd_megakernel4Args
		.amdhsa_group_segment_fixed_size 0
		.amdhsa_private_segment_fixed_size 0
		.amdhsa_kernarg_size 520
		.amdhsa_user_sgpr_count 2
		.amdhsa_user_sgpr_dispatch_ptr 0
		.amdhsa_user_sgpr_queue_ptr 0
		.amdhsa_user_sgpr_kernarg_segment_ptr 1
		.amdhsa_user_sgpr_dispatch_id 0
		.amdhsa_user_sgpr_kernarg_preload_length 0
		.amdhsa_user_sgpr_kernarg_preload_offset 0
		.amdhsa_user_sgpr_private_segment_size 0
		.amdhsa_uses_dynamic_stack 0
		.amdhsa_enable_private_segment 0
		.amdhsa_system_sgpr_workgroup_id_x 1
		.amdhsa_system_sgpr_workgroup_id_y 0
		.amdhsa_system_sgpr_workgroup_id_z 0
		.amdhsa_system_sgpr_workgroup_info 0
		.amdhsa_system_vgpr_workitem_id 2
		.amdhsa_next_free_vgpr 255
		.amdhsa_next_free_sgpr 102
		.amdhsa_accum_offset 256
		.amdhsa_reserve_vcc 1
		.amdhsa_float_round_mode_32 0
		.amdhsa_float_round_mode_16_64 0
		.amdhsa_float_denorm_mode_32 3
		.amdhsa_float_denorm_mode_16_64 3
		.amdhsa_dx10_clamp 1
		.amdhsa_ieee_mode 1
		.amdhsa_fp16_overflow 0
		.amdhsa_tg_split 0
		.amdhsa_exception_fp_ieee_invalid_op 0
		.amdhsa_exception_fp_denorm_src 0
		.amdhsa_exception_fp_ieee_div_zero 0
		.amdhsa_exception_fp_ieee_overflow 0
		.amdhsa_exception_fp_ieee_underflow 0
		.amdhsa_exception_fp_ieee_inexact 0
		.amdhsa_exception_int_div_zero 0
	.end_amdhsa_kernel

; #define LAS __attribute__((address_space(3)))
; __global__ void __launch_bounds__(512, 2) fwd_megakernel(Args a) {
;     extern __shared__ __attribute__((aligned(16))) unsigned char shm[];
;     LAS unsigned char* lds = (LAS unsigned char*)shm;
amdhsa.kernels:
  - .agpr_count:     0
    .args:
      - .offset:         0
        .size:           264
        .value_kind:     by_value
      - .offset:         264
        .size:           4
        .value_kind:     hidden_block_count_x
      - .offset:         268
        .size:           4
        .value_kind:     hidden_block_count_y
      - .offset:         272
        .size:           4
        .value_kind:     hidden_block_count_z
      - .offset:         276
        .size:           2
        .value_kind:     hidden_group_size_x
      - .offset:         278
        .size:           2
        .value_kind:     hidden_group_size_y
      - .offset:         280
        .size:           2
        .value_kind:     hidden_group_size_z
      - .offset:         282
        .size:           2
        .value_kind:     hidden_remainder_x
      - .offset:         284
        .size:           2
        .value_kind:     hidden_remainder_y
      - .offset:         286
        .size:           2
        .value_kind:     hidden_remainder_z
      - .offset:         304
        .size:           8
        .value_kind:     hidden_global_offset_x
      - .offset:         312
        .size:           8
        .value_kind:     hidden_global_offset_y
      - .offset:         320
        .size:           8
        .value_kind:     hidden_global_offset_z
      - .offset:         328
        .size:           2
        .value_kind:     hidden_grid_dims
      - .offset:         352
        .size:           8
        .value_kind:     hidden_multigrid_sync_arg
      - .offset:         384
        .size:           4
        .value_kind:     hidden_dynamic_lds_size
    .group_segment_fixed_size: 0
    .kernarg_segment_align: 8
    .kernarg_segment_size: 520
    .language:       OpenCL C
    .language_version:
      - 2
      - 0
    .max_flat_workgroup_size: 512
    .name:           _Z14fwd_megakernel4Args
    .private_segment_fixed_size: 0
    .sgpr_count:     108
    .sgpr_spill_count: 243
    .symbol:         _Z14fwd_megakernel4Args.kd
    .uniform_work_group_size: 1
    .uses_dynamic_stack: false
    .vgpr_count:     255
    .vgpr_spill_count: 0
    .wavefront_size: 64
